# P1 latent rows: the table barrier moved to the first iteration's first table read, so the four waves without table work start streaming rows while the tables are built
# speedup vs baseline: 1.0233x; 1.0021x over previous
.LBB0_151:
	s_add_i32 s6, s60, s14
	s_cmp_ge_i32 s6, s12
	s_waitcnt lgkmcnt(0)
	s_cbranch_scc0 .Lp1_rows
	s_barrier
	s_branch .LBB0_154
.Lp1_rows:
	s_mov_b32 s97, 1
	v_mbcnt_lo_u32_b32 v1, -1, 0
	v_mbcnt_hi_u32_b32 v1, -1, v1
	v_and_b32_e32 v2, 64, v1
	v_add_u32_e32 v2, 64, v2
	s_waitcnt vmcnt(0)
	v_xor_b32_e32 v4, 1, v1
	v_cmp_lt_i32_e32 vcc, v4, v2
	s_ashr_i32 s7, s6, 31
	s_lshl_b32 s4, s6, 2
	v_cndmask_b32_e32 v4, v1, v4, vcc
	v_lshlrev_b32_e32 v66, 2, v4
	v_xor_b32_e32 v4, 2, v1
	v_cmp_lt_i32_e32 vcc, v4, v2
	s_lshl_b64 s[14:15], s[6:7], 14
	v_lshlrev_b32_e32 v0, 2, v130
	v_cndmask_b32_e32 v4, v1, v4, vcc
	v_lshlrev_b32_e32 v67, 2, v4
	v_xor_b32_e32 v4, 4, v1
	v_cmp_lt_i32_e32 vcc, v4, v2
	s_add_u32 s14, s52, s14
	v_mov_b32_e32 v3, 0
	v_cndmask_b32_e32 v4, v1, v4, vcc
	v_lshlrev_b32_e32 v68, 2, v4
	v_xor_b32_e32 v4, 8, v1
	v_cmp_lt_i32_e32 vcc, v4, v2
	v_or_b32_e32 v6, 0x200, v0
	v_or_b32_e32 v8, 0x300, v0
	v_cndmask_b32_e32 v4, v1, v4, vcc
	v_lshlrev_b32_e32 v69, 2, v4
	v_xor_b32_e32 v4, 16, v1
	v_cmp_lt_i32_e32 vcc, v4, v2
	s_addc_u32 s15, s53, s15
	s_movk_i32 s5, 0x2000
	v_cndmask_b32_e32 v4, v1, v4, vcc
	v_lshlrev_b32_e32 v70, 2, v4
	v_xor_b32_e32 v4, 32, v1
	v_cmp_lt_i32_e32 vcc, v4, v2
	v_lshlrev_b32_e32 v2, 4, v130
	v_lshl_add_u64 v[64:65], s[14:15], 0, v[2:3]
	v_cndmask_b32_e32 v1, v1, v4, vcc
	v_or_b32_e32 v4, 0x100, v0
	v_lshlrev_b32_e32 v71, 2, v1
	s_add_i32 s7, 0, 0x2000
	s_movk_i32 s9, 0x1000
	s_add_i32 s11, 0, 0x1000
	s_movk_i32 s13, 0x3000
	s_add_i32 s80, 0, 0x3000
	v_lshlrev_b32_e32 v72, 2, v0
	v_mov_b32_e32 v73, 0x358637bd
	v_lshlrev_b32_e32 v74, 1, v0
	v_lshlrev_b32_e32 v75, 1, v4
	v_lshlrev_b32_e32 v76, 1, v6
	v_lshlrev_b32_e32 v77, 1, v8
	s_mov_b64 s[14:15], 0x20000
.LBB0_153:
	v_add_co_u32_e32 v0, vcc, s9, v64
	global_load_dwordx4 v[16:19], v[64:65], off nt
	global_load_dwordx4 v[12:15], v[64:65], off offset:1024 nt
	global_load_dwordx4 v[8:11], v[64:65], off offset:2048 nt
	global_load_dwordx4 v[4:7], v[64:65], off offset:3072 nt
	v_addc_co_u32_e32 v1, vcc, 0, v65, vcc
	v_add_co_u32_e32 v2, vcc, s5, v64
	s_ashr_i32 s18, s6, 10
	s_nop 0
	v_addc_co_u32_e32 v3, vcc, 0, v65, vcc
	v_add_co_u32_e32 v32, vcc, s13, v64
	s_and_b32 s19, s4, 0xffc
	s_nop 0
	v_addc_co_u32_e32 v33, vcc, 0, v65, vcc
	global_load_dwordx4 v[60:63], v[2:3], off offset:-4096 nt
	global_load_dwordx4 v[52:55], v[0:1], off offset:1024 nt
	global_load_dwordx4 v[44:47], v[0:1], off offset:3072 nt
	global_load_dwordx4 v[56:59], v[0:1], off offset:2048 nt
	global_load_dwordx4 v[48:51], v[2:3], off nt
	global_load_dwordx4 v[36:39], v[2:3], off offset:1024 nt
	global_load_dwordx4 v[20:23], v[2:3], off offset:3072 nt
	global_load_dwordx4 v[40:43], v[2:3], off offset:2048 nt
	global_load_dwordx4 v[28:31], v[32:33], off nt
	global_load_dwordx4 v[24:27], v[32:33], off offset:1024 nt
	s_nop 0
	global_load_dwordx4 v[0:3], v[32:33], off offset:3072 nt
	s_nop 0
	global_load_dwordx4 v[32:35], v[32:33], off offset:2048 nt
	s_mul_i32 s55, s18, 0x1100
	s_mul_hi_i32 s54, s18, 0x1100
	s_add_u32 s58, s55, s19
	s_addc_u32 s59, s54, 0
	s_lshl_b64 s[54:55], s[58:59], 11
	s_add_u32 s58, s40, s54
	s_addc_u32 s59, s41, s55
	s_cmp_eq_u32 s18, s3
	s_cselect_b32 s19, s11, s80
	v_add_u32_e32 v133, s19, v72
	s_cselect_b32 s18, 0, s7
	v_add_u32_e32 v131, s18, v72
	s_cmp_eq_u32 s97, 0
	s_cbranch_scc1 .Lp1_nobar
	s_barrier
	s_mov_b32 s97, 0
.Lp1_nobar:
	ds_read_b128 v[78:81], v131
	ds_read_b128 v[82:85], v133
	s_add_u32 s54, s58, 0x1000
	s_addc_u32 s55, s59, 0
	s_add_u32 s18, s58, 0x1800
	s_addc_u32 s19, s59, 0
	s_add_i32 s6, s6, 8
	s_add_i32 s4, s4, 32
	v_lshl_add_u64 v[64:65], v[64:65], 0, s[14:15]
	s_cmp_ge_i32 s6, s12
	s_waitcnt vmcnt(15)
	v_pk_mul_f32 v[86:87], v[18:19], v[18:19]
	v_pk_mul_f32 v[88:89], v[16:17], v[16:17]
	s_waitcnt vmcnt(14)
	v_pk_mul_f32 v[90:91], v[14:15], v[14:15]
	v_pk_mul_f32 v[92:93], v[12:13], v[12:13]
	s_waitcnt vmcnt(13)
	v_mul_f32_e32 v94, v9, v9
	v_mul_f32_e32 v96, v11, v11
	v_pk_mov_b32 v[98:99], v[88:89], v[86:87] op_sel:[1,0]
	v_mov_b32_e32 v89, v87
	v_pk_mov_b32 v[86:87], v[92:93], v[90:91] op_sel:[1,0]
	v_mov_b32_e32 v93, v91
	s_waitcnt vmcnt(12)
	v_mul_f32_e32 v107, v6, v6
	v_mul_f32_e32 v109, v7, v7
	v_pk_fma_f32 v[90:91], v[8:9], v[8:9], v[94:95] op_sel_hi:[1,1,0]
	v_pk_fma_f32 v[94:95], v[10:11], v[10:11], v[96:97] op_sel_hi:[1,1,0]
	s_waitcnt vmcnt(11)
	v_pk_mul_f32 v[96:97], v[62:63], v[62:63]
	v_pk_mul_f32 v[100:101], v[60:61], v[60:61]
	s_waitcnt vmcnt(10)
	v_pk_mul_f32 v[102:103], v[54:55], v[54:55]
	v_pk_mul_f32 v[104:105], v[52:53], v[52:53]
	s_waitcnt vmcnt(8)
	v_mul_f32_e32 v106, v57, v57
	v_mul_f32_e32 v108, v59, v59
	s_waitcnt vmcnt(7)
	v_pk_mul_f32 v[110:111], v[50:51], v[50:51]
	v_pk_mul_f32 v[112:113], v[48:49], v[48:49]
	s_waitcnt vmcnt(6)
	v_pk_mul_f32 v[114:115], v[38:39], v[38:39]
	v_pk_mul_f32 v[116:117], v[36:37], v[36:37]
	s_waitcnt vmcnt(4)
	v_mul_f32_e32 v118, v41, v41
	v_mul_f32_e32 v120, v43, v43
	s_waitcnt vmcnt(3)
	v_pk_mul_f32 v[122:123], v[30:31], v[30:31]
	v_pk_mul_f32 v[124:125], v[28:29], v[28:29]
	s_waitcnt vmcnt(2)
	v_pk_mul_f32 v[126:127], v[26:27], v[26:27]
	v_pk_mul_f32 v[128:129], v[24:25], v[24:25]
	v_pk_add_f32 v[88:89], v[98:99], v[88:89]
	v_pk_add_f32 v[86:87], v[86:87], v[92:93]
	v_mul_f32_e32 v135, v4, v4
	v_mul_f32_e32 v137, v5, v5
	v_mov_b32_e32 v91, v107
	v_mov_b32_e32 v95, v109
	v_pk_mov_b32 v[92:93], v[100:101], v[96:97] op_sel:[1,0]
	v_mov_b32_e32 v101, v97
	v_pk_mov_b32 v[96:97], v[104:105], v[102:103] op_sel:[1,0]
	v_mov_b32_e32 v105, v103
	v_pk_fma_f32 v[98:99], v[56:57], v[56:57], v[106:107] op_sel_hi:[1,1,0]
	v_pk_fma_f32 v[102:103], v[58:59], v[58:59], v[108:109] op_sel_hi:[1,1,0]
	v_pk_mov_b32 v[106:107], v[112:113], v[110:111] op_sel:[1,0]
	v_mov_b32_e32 v113, v111
	v_pk_mov_b32 v[108:109], v[116:117], v[114:115] op_sel:[1,0]
	v_mov_b32_e32 v117, v115
	v_pk_fma_f32 v[110:111], v[40:41], v[40:41], v[118:119] op_sel_hi:[1,1,0]
	v_pk_fma_f32 v[114:115], v[42:43], v[42:43], v[120:121] op_sel_hi:[1,1,0]
	v_pk_mov_b32 v[118:119], v[124:125], v[122:123] op_sel:[1,0]
	v_mov_b32_e32 v125, v123
	v_pk_mov_b32 v[120:121], v[128:129], v[126:127] op_sel:[1,0]
	v_mov_b32_e32 v129, v127
	v_pk_add_f32 v[88:89], v[88:89], v[88:89] op_sel:[0,1] op_sel_hi:[1,0]
	v_pk_add_f32 v[86:87], v[86:87], v[86:87] op_sel:[0,1] op_sel_hi:[1,0]
	s_waitcnt vmcnt(0)
	v_mul_f32_e32 v132, v33, v33
	v_mul_f32_e32 v136, v35, v35
	v_pk_add_f32 v[90:91], v[90:91], v[94:95]
	v_pk_add_f32 v[92:93], v[92:93], v[100:101]
	v_pk_add_f32 v[94:95], v[96:97], v[104:105]
	v_pk_add_f32 v[96:97], v[106:107], v[112:113]
	v_pk_add_f32 v[100:101], v[108:109], v[116:117]
	v_pk_add_f32 v[104:105], v[118:119], v[124:125]
	v_pk_add_f32 v[106:107], v[120:121], v[128:129]
	v_mov_b32_e32 v89, v135
	v_mov_b32_e32 v87, v137
	v_mul_f32_e32 v138, v44, v44
	v_mul_f32_e32 v139, v45, v45
	v_mul_f32_e32 v140, v46, v46
	v_mul_f32_e32 v141, v47, v47
	v_mul_f32_e32 v142, v20, v20
	v_mul_f32_e32 v143, v21, v21
	v_mul_f32_e32 v144, v22, v22
	v_mul_f32_e32 v145, v23, v23
	v_mul_f32_e32 v146, v0, v0
	v_mul_f32_e32 v147, v1, v1
	v_mul_f32_e32 v148, v2, v2
	v_mul_f32_e32 v149, v3, v3
	v_pk_fma_f32 v[122:123], v[32:33], v[32:33], v[132:133] op_sel_hi:[1,1,0]
	v_pk_fma_f32 v[126:127], v[34:35], v[34:35], v[136:137] op_sel_hi:[1,1,0]
	v_pk_add_f32 v[92:93], v[92:93], v[92:93] op_sel:[0,1] op_sel_hi:[1,0]
	v_pk_add_f32 v[94:95], v[94:95], v[94:95] op_sel:[0,1] op_sel_hi:[1,0]
	v_pk_add_f32 v[96:97], v[96:97], v[96:97] op_sel:[0,1] op_sel_hi:[1,0]
	v_pk_add_f32 v[100:101], v[100:101], v[100:101] op_sel:[0,1] op_sel_hi:[1,0]
	v_pk_add_f32 v[104:105], v[104:105], v[104:105] op_sel:[0,1] op_sel_hi:[1,0]
	v_pk_add_f32 v[106:107], v[106:107], v[106:107] op_sel:[0,1] op_sel_hi:[1,0]
	v_pk_add_f32 v[86:87], v[88:89], v[86:87]
	v_mov_b32_e32 v99, v140
	v_mov_b32_e32 v103, v141
	v_mov_b32_e32 v111, v144
	v_mov_b32_e32 v115, v145
	v_mov_b32_e32 v123, v148
	v_mov_b32_e32 v127, v149
	v_mov_b32_e32 v93, v138
	v_mov_b32_e32 v95, v139
	v_mov_b32_e32 v97, v142
	v_mov_b32_e32 v101, v143
	v_mov_b32_e32 v105, v146
	v_mov_b32_e32 v107, v147
	v_pk_add_f32 v[86:87], v[86:87], v[90:91]
	v_pk_add_f32 v[98:99], v[98:99], v[102:103]
	v_pk_add_f32 v[102:103], v[110:111], v[114:115]
	v_pk_add_f32 v[108:109], v[122:123], v[126:127]
	v_pk_add_f32 v[88:89], v[92:93], v[94:95]
	v_pk_add_f32 v[90:91], v[96:97], v[100:101]
	v_pk_add_f32 v[92:93], v[104:105], v[106:107]
	v_add_f32_e32 v94, v86, v87
	v_pk_add_f32 v[86:87], v[88:89], v[98:99]
	v_pk_add_f32 v[88:89], v[90:91], v[102:103]
	v_pk_add_f32 v[90:91], v[92:93], v[108:109]
	ds_bpermute_b32 v92, v66, v94
	v_add_f32_e32 v86, v86, v87
	v_add_f32_e32 v87, v88, v89
	v_add_f32_e32 v88, v90, v91
	ds_bpermute_b32 v89, v66, v86
	ds_bpermute_b32 v91, v66, v88
	ds_bpermute_b32 v90, v66, v87
	s_waitcnt lgkmcnt(3)
	v_add_f32_e32 v92, v94, v92
	ds_bpermute_b32 v93, v67, v92
	s_waitcnt lgkmcnt(3)
	v_add_f32_e32 v86, v86, v89
	s_waitcnt lgkmcnt(2)
	v_add_f32_e32 v88, v88, v91
	ds_bpermute_b32 v89, v67, v86
	s_waitcnt lgkmcnt(2)
	v_add_f32_e32 v87, v87, v90
	ds_bpermute_b32 v91, v67, v88
	ds_bpermute_b32 v90, v67, v87
	s_waitcnt lgkmcnt(3)
	v_add_f32_e32 v92, v92, v93
	ds_bpermute_b32 v93, v68, v92
	s_waitcnt lgkmcnt(3)
	v_add_f32_e32 v86, v86, v89
	s_waitcnt lgkmcnt(2)
	v_add_f32_e32 v88, v88, v91
	ds_bpermute_b32 v89, v68, v86
	s_waitcnt lgkmcnt(2)
	v_add_f32_e32 v87, v87, v90
	ds_bpermute_b32 v91, v68, v88
	ds_bpermute_b32 v90, v68, v87
	s_waitcnt lgkmcnt(3)
	v_add_f32_e32 v92, v92, v93
	ds_bpermute_b32 v93, v69, v92
	s_waitcnt lgkmcnt(3)
	v_add_f32_e32 v86, v86, v89
	s_waitcnt lgkmcnt(2)
	v_add_f32_e32 v88, v88, v91
	ds_bpermute_b32 v89, v69, v86
	s_waitcnt lgkmcnt(2)
	v_add_f32_e32 v87, v87, v90
	ds_bpermute_b32 v91, v69, v88
	ds_bpermute_b32 v90, v69, v87
	s_waitcnt lgkmcnt(3)
	v_add_f32_e32 v92, v92, v93
	ds_bpermute_b32 v93, v70, v92
	s_waitcnt lgkmcnt(3)
	v_add_f32_e32 v86, v86, v89
	s_waitcnt lgkmcnt(2)
	v_add_f32_e32 v88, v88, v91
	ds_bpermute_b32 v89, v70, v86
	s_waitcnt lgkmcnt(2)
	v_add_f32_e32 v87, v87, v90
	ds_bpermute_b32 v91, v70, v88
	ds_bpermute_b32 v90, v70, v87
	s_waitcnt lgkmcnt(3)
	v_add_f32_e32 v92, v92, v93
	ds_bpermute_b32 v93, v71, v92
	s_waitcnt lgkmcnt(3)
	v_add_f32_e32 v86, v86, v89
	s_waitcnt lgkmcnt(2)
	v_add_f32_e32 v88, v88, v91
	ds_bpermute_b32 v89, v71, v86
	s_waitcnt lgkmcnt(2)
	v_add_f32_e32 v87, v87, v90
	ds_bpermute_b32 v91, v71, v88
	ds_bpermute_b32 v90, v71, v87
	s_waitcnt lgkmcnt(3)
	v_add_f32_e32 v92, v92, v93
	v_fmamk_f32 v92, v92, 0x3a800000, v73
	s_waitcnt lgkmcnt(2)
	v_add_f32_e32 v89, v86, v89
	v_rsq_f32_e32 v86, v92
	s_waitcnt lgkmcnt(1)
	v_add_f32_e32 v88, v88, v91
	v_fmamk_f32 v89, v89, 0x3a800000, v73
	s_waitcnt lgkmcnt(0)
	v_add_f32_e32 v87, v87, v90
	v_fmamk_f32 v91, v88, 0x3a800000, v73
	v_rsq_f32_e32 v88, v89
	v_fmamk_f32 v87, v87, 0x3a800000, v73
	v_pk_mul_f32 v[16:17], v[16:17], v[86:87] op_sel_hi:[1,0]
	v_pk_mul_f32 v[18:19], v[18:19], v[86:87] op_sel_hi:[1,0]
	v_rsq_f32_e32 v90, v87
	v_pk_mul_f32 v[12:13], v[12:13], v[86:87] op_sel_hi:[1,0]
	v_pk_mul_f32 v[14:15], v[14:15], v[86:87] op_sel_hi:[1,0]
	v_pk_mul_f32 v[94:95], v[8:9], v[86:87] op_sel_hi:[1,0]
	v_pk_mul_f32 v[96:97], v[10:11], v[86:87] op_sel_hi:[1,0]
	v_pk_mul_f32 v[98:99], v[4:5], v[86:87] op_sel_hi:[1,0]
	v_pk_mul_f32 v[86:87], v[6:7], v[86:87] op_sel_hi:[1,0]
	v_pk_fma_f32 v[4:5], v[80:81], v[18:19], v[84:85]
	v_pk_fma_f32 v[6:7], v[78:79], v[16:17], v[82:83]
	v_pk_mul_f32 v[16:17], v[60:61], v[88:89] op_sel_hi:[1,0]
	v_cvt_pk_bf16_f32 v60, v6, v7
	v_cvt_pk_bf16_f32 v61, v4, v5
	ds_read_b128 v[4:7], v131 offset:1024
	ds_read_b128 v[8:11], v133 offset:1024
	global_store_dwordx2 v74, v[60:61], s[58:59]
	v_pk_mul_f32 v[18:19], v[62:63], v[88:89] op_sel_hi:[1,0]
	v_pk_mul_f32 v[52:53], v[52:53], v[88:89] op_sel_hi:[1,0]
	v_pk_mul_f32 v[54:55], v[54:55], v[88:89] op_sel_hi:[1,0]
	s_waitcnt lgkmcnt(0)
	v_pk_fma_f32 v[6:7], v[6:7], v[14:15], v[10:11]
	v_pk_fma_f32 v[4:5], v[4:5], v[12:13], v[8:9]
	v_pk_mul_f32 v[56:57], v[56:57], v[88:89] op_sel_hi:[1,0]
	v_cvt_pk_bf16_f32 v12, v4, v5
	v_cvt_pk_bf16_f32 v13, v6, v7
	ds_read_b128 v[4:7], v131 offset:2048
	ds_read_b128 v[8:11], v133 offset:2048
	global_store_dwordx2 v74, v[12:13], s[58:59] offset:512
	v_pk_mul_f32 v[58:59], v[58:59], v[88:89] op_sel_hi:[1,0]
	v_pk_mul_f32 v[44:45], v[44:45], v[88:89] op_sel_hi:[1,0]
	v_pk_mul_f32 v[46:47], v[46:47], v[88:89] op_sel_hi:[1,0]
	s_waitcnt lgkmcnt(0)
	v_pk_fma_f32 v[6:7], v[96:97], v[6:7], v[10:11]
	v_pk_fma_f32 v[4:5], v[94:95], v[4:5], v[8:9]
	v_pk_mul_f32 v[48:49], v[48:49], v[90:91] op_sel_hi:[1,0]
	v_cvt_pk_bf16_f32 v12, v4, v5
	v_cvt_pk_bf16_f32 v13, v6, v7
	ds_read_b128 v[4:7], v131 offset:3072
	ds_read_b128 v[8:11], v133 offset:3072
	global_store_dwordx2 v74, v[12:13], s[58:59] offset:1024
	v_pk_mul_f32 v[50:51], v[50:51], v[90:91] op_sel_hi:[1,0]
	v_pk_mul_f32 v[36:37], v[36:37], v[90:91] op_sel_hi:[1,0]
	v_pk_mul_f32 v[38:39], v[38:39], v[90:91] op_sel_hi:[1,0]
	s_waitcnt lgkmcnt(0)
	v_pk_fma_f32 v[6:7], v[86:87], v[6:7], v[10:11]
	v_pk_fma_f32 v[4:5], v[98:99], v[4:5], v[8:9]
	v_pk_mul_f32 v[40:41], v[40:41], v[90:91] op_sel_hi:[1,0]
	v_cvt_pk_bf16_f32 v12, v4, v5
	v_cvt_pk_bf16_f32 v13, v6, v7
	ds_read_b128 v[4:7], v131
	ds_read_b128 v[8:11], v133
	global_store_dwordx2 v74, v[12:13], s[58:59] offset:1536
	v_pk_mul_f32 v[42:43], v[42:43], v[90:91] op_sel_hi:[1,0]
	v_pk_mul_f32 v[20:21], v[20:21], v[90:91] op_sel_hi:[1,0]
	v_pk_mul_f32 v[22:23], v[22:23], v[90:91] op_sel_hi:[1,0]
	s_waitcnt lgkmcnt(0)
	v_pk_fma_f32 v[6:7], v[6:7], v[18:19], v[10:11]
	v_pk_fma_f32 v[4:5], v[4:5], v[16:17], v[8:9]
	v_rsq_f32_e32 v92, v91
	v_cvt_pk_bf16_f32 v12, v4, v5
	v_cvt_pk_bf16_f32 v13, v6, v7
	ds_read_b128 v[4:7], v131 offset:1024
	ds_read_b128 v[8:11], v133 offset:1024
	global_store_dwordx2 v74, v[12:13], s[58:59] offset:2048
	v_pk_mul_f32 v[28:29], v[28:29], v[92:93] op_sel_hi:[1,0]
	v_pk_mul_f32 v[30:31], v[30:31], v[92:93] op_sel_hi:[1,0]
	v_pk_mul_f32 v[24:25], v[24:25], v[92:93] op_sel_hi:[1,0]
	s_waitcnt lgkmcnt(0)
	v_pk_fma_f32 v[6:7], v[6:7], v[54:55], v[10:11]
	v_pk_fma_f32 v[4:5], v[4:5], v[52:53], v[8:9]
	v_pk_mul_f32 v[26:27], v[26:27], v[92:93] op_sel_hi:[1,0]
	v_cvt_pk_bf16_f32 v12, v4, v5
	v_cvt_pk_bf16_f32 v13, v6, v7
	ds_read_b128 v[4:7], v131 offset:2048
	ds_read_b128 v[8:11], v133 offset:2048
	global_store_dwordx2 v74, v[12:13], s[58:59] offset:2560
	v_pk_mul_f32 v[32:33], v[32:33], v[92:93] op_sel_hi:[1,0]
	v_pk_mul_f32 v[34:35], v[34:35], v[92:93] op_sel_hi:[1,0]
	v_pk_mul_f32 v[0:1], v[0:1], v[92:93] op_sel_hi:[1,0]
	s_waitcnt lgkmcnt(0)
	v_pk_fma_f32 v[6:7], v[58:59], v[6:7], v[10:11]
	v_pk_fma_f32 v[4:5], v[56:57], v[4:5], v[8:9]
	v_pk_mul_f32 v[2:3], v[2:3], v[92:93] op_sel_hi:[1,0]
	v_cvt_pk_bf16_f32 v12, v4, v5
	v_cvt_pk_bf16_f32 v13, v6, v7
	ds_read_b128 v[4:7], v131 offset:3072
	ds_read_b128 v[8:11], v133 offset:3072
	global_store_dwordx2 v74, v[12:13], s[58:59] offset:3072
	s_waitcnt lgkmcnt(0)
	v_pk_fma_f32 v[6:7], v[46:47], v[6:7], v[10:11]
	v_pk_fma_f32 v[4:5], v[44:45], v[4:5], v[8:9]
	s_nop 0
	v_cvt_pk_bf16_f32 v12, v4, v5
	v_cvt_pk_bf16_f32 v13, v6, v7
	ds_read_b128 v[4:7], v131
	ds_read_b128 v[8:11], v133
	global_store_dwordx2 v74, v[12:13], s[58:59] offset:3584
	s_waitcnt lgkmcnt(0)
	v_pk_fma_f32 v[6:7], v[6:7], v[50:51], v[10:11]
	v_pk_fma_f32 v[4:5], v[4:5], v[48:49], v[8:9]
	s_nop 0
	v_cvt_pk_bf16_f32 v12, v4, v5
	v_cvt_pk_bf16_f32 v13, v6, v7
	ds_read_b128 v[4:7], v131 offset:1024
	ds_read_b128 v[8:11], v133 offset:1024
	global_store_dwordx2 v74, v[12:13], s[54:55]
	s_waitcnt lgkmcnt(0)
	v_pk_fma_f32 v[6:7], v[6:7], v[38:39], v[10:11]
	v_pk_fma_f32 v[4:5], v[4:5], v[36:37], v[8:9]
	s_nop 0
	v_cvt_pk_bf16_f32 v12, v4, v5
	v_cvt_pk_bf16_f32 v13, v6, v7
	ds_read_b128 v[4:7], v131 offset:2048
	ds_read_b128 v[8:11], v133 offset:2048
	global_store_dwordx2 v75, v[12:13], s[54:55]
	s_waitcnt lgkmcnt(0)
	v_pk_fma_f32 v[6:7], v[42:43], v[6:7], v[10:11]
	v_pk_fma_f32 v[4:5], v[40:41], v[4:5], v[8:9]
	s_nop 0
	v_cvt_pk_bf16_f32 v12, v4, v5
	v_cvt_pk_bf16_f32 v13, v6, v7
	ds_read_b128 v[4:7], v131 offset:3072
	ds_read_b128 v[8:11], v133 offset:3072
	global_store_dwordx2 v76, v[12:13], s[54:55]
	s_waitcnt lgkmcnt(0)
	v_pk_fma_f32 v[6:7], v[22:23], v[6:7], v[10:11]
	v_pk_fma_f32 v[4:5], v[20:21], v[4:5], v[8:9]
	s_nop 0
	v_cvt_pk_bf16_f32 v12, v4, v5
	v_cvt_pk_bf16_f32 v13, v6, v7
	ds_read_b128 v[4:7], v131
	ds_read_b128 v[8:11], v133
	global_store_dwordx2 v77, v[12:13], s[54:55]
	s_waitcnt lgkmcnt(0)
	v_pk_fma_f32 v[6:7], v[6:7], v[30:31], v[10:11]
	v_pk_fma_f32 v[4:5], v[4:5], v[28:29], v[8:9]
	s_nop 0
	v_cvt_pk_bf16_f32 v12, v4, v5
	v_cvt_pk_bf16_f32 v13, v6, v7
	ds_read_b128 v[4:7], v131 offset:1024
	ds_read_b128 v[8:11], v133 offset:1024
	global_store_dwordx2 v74, v[12:13], s[18:19]
	s_waitcnt lgkmcnt(0)
	v_pk_fma_f32 v[6:7], v[6:7], v[26:27], v[10:11]
	v_pk_fma_f32 v[4:5], v[4:5], v[24:25], v[8:9]
	s_nop 0
	v_cvt_pk_bf16_f32 v12, v4, v5
	v_cvt_pk_bf16_f32 v13, v6, v7
	ds_read_b128 v[4:7], v131 offset:2048
	ds_read_b128 v[8:11], v133 offset:2048
	global_store_dwordx2 v75, v[12:13], s[18:19]
	s_waitcnt lgkmcnt(0)
	v_pk_fma_f32 v[6:7], v[34:35], v[6:7], v[10:11]
	v_pk_fma_f32 v[4:5], v[32:33], v[4:5], v[8:9]
	s_nop 0
	v_cvt_pk_bf16_f32 v12, v4, v5
	v_cvt_pk_bf16_f32 v13, v6, v7
	ds_read_b128 v[4:7], v131 offset:3072
	ds_read_b128 v[8:11], v133 offset:3072
	global_store_dwordx2 v76, v[12:13], s[18:19]
	s_waitcnt lgkmcnt(0)
	v_pk_fma_f32 v[0:1], v[0:1], v[4:5], v[8:9]
	v_pk_fma_f32 v[2:3], v[2:3], v[6:7], v[10:11]
	v_cvt_pk_bf16_f32 v0, v0, v1
	s_nop 0
	v_cvt_pk_bf16_f32 v1, v2, v3
	global_store_dwordx2 v77, v[0:1], s[18:19]
	s_cbranch_scc0 .LBB0_153
